# added: accumulator zero-init with v_mov_b64 pairs
# speedup vs baseline: 1.0021x; 1.0021x over previous
.LBB0_205:
	s_ashr_i32 s63, s62, 31
	s_lshl_b64 s[64:65], s[62:63], 19
	s_add_u32 s64, s44, s64
	s_addc_u32 s65, s45, s65
	s_and_b64 s[70:71], s[4:5], exec
	v_readlane_b32 s70, v255, 12
	v_readlane_b32 s76, v255, 14
	s_cselect_b32 s37, s65, s47
	s_cselect_b32 s63, s64, s46
	s_cmp_gt_i32 s62, 63
	v_readlane_b32 s71, v255, 13
	v_readlane_b32 s77, v255, 15
	s_cselect_b32 s72, s77, s71
	s_cselect_b32 s73, s76, s70
	s_ashr_i32 s61, s60, 31
	s_lshl_b64 s[70:71], s[60:61], 19
	s_add_u32 s70, s73, s70
	s_addc_u32 s71, s72, s71
	s_and_b64 s[72:73], s[4:5], exec
	s_cselect_b32 s61, s71, s75
	s_cselect_b32 s73, s70, s74
	s_cmp_gt_i32 s6, 63
	s_cselect_b32 s76, 0x1400, 0
	s_lshl_b32 s72, s36, 8
	s_add_i32 s76, s76, s72
	v_or_b32_e32 v0, s76, v171
	v_ashrrev_i32_e32 v1, 31, v0
	s_add_u32 s46, s46, 0x40080
	v_lshlrev_b64 v[0:1], 2, v[0:1]
	s_addc_u32 s47, s47, 0
	v_lshl_add_u64 v[128:129], s[10:11], 0, v[0:1]
	v_lshl_add_u64 v[130:131], s[0:1], 0, v[0:1]
	s_add_u32 s88, s74, 0x100
	v_mov_b32_e32 v0, 0
	s_addc_u32 s89, s75, 0
	s_mov_b32 s90, -2
	v_mov_b32_e32 v1, v0
	v_mov_b64_e32 v[2:3], 0
	v_mov_b64_e32 v[4:5], 0
	v_mov_b64_e32 v[6:7], 0
	v_mov_b64_e32 v[16:17], 0
	v_mov_b64_e32 v[18:19], 0
	v_mov_b64_e32 v[20:21], 0
	v_mov_b64_e32 v[22:23], 0
	v_mov_b64_e32 v[32:33], 0
	v_mov_b64_e32 v[34:35], 0
	v_mov_b64_e32 v[36:37], 0
	v_mov_b64_e32 v[38:39], 0
	v_mov_b64_e32 v[48:49], 0
	v_mov_b64_e32 v[50:51], 0
	v_mov_b64_e32 v[52:53], 0
	v_mov_b64_e32 v[54:55], 0
	v_mov_b64_e32 v[8:9], 0
	v_mov_b64_e32 v[10:11], 0
	v_mov_b64_e32 v[12:13], 0
	v_mov_b64_e32 v[14:15], 0
	v_mov_b64_e32 v[24:25], 0
	v_mov_b64_e32 v[26:27], 0
	v_mov_b64_e32 v[28:29], 0
	v_mov_b64_e32 v[30:31], 0
	v_mov_b64_e32 v[40:41], 0
	v_mov_b64_e32 v[42:43], 0
	v_mov_b64_e32 v[44:45], 0
	v_mov_b64_e32 v[46:47], 0
	v_mov_b64_e32 v[56:57], 0
	v_mov_b64_e32 v[58:59], 0
	v_mov_b64_e32 v[60:61], 0
	v_mov_b64_e32 v[62:63], 0
	v_mov_b64_e32 v[64:65], 0
	v_mov_b64_e32 v[66:67], 0
	v_mov_b64_e32 v[68:69], 0
	v_mov_b64_e32 v[70:71], 0
	v_mov_b64_e32 v[80:81], 0
	v_mov_b64_e32 v[82:83], 0
	v_mov_b64_e32 v[84:85], 0
	v_mov_b64_e32 v[86:87], 0
	v_mov_b64_e32 v[96:97], 0
	v_mov_b64_e32 v[98:99], 0
	v_mov_b64_e32 v[100:101], 0
	v_mov_b64_e32 v[102:103], 0
	v_mov_b64_e32 v[112:113], 0
	v_mov_b64_e32 v[114:115], 0
	v_mov_b64_e32 v[116:117], 0
	v_mov_b64_e32 v[118:119], 0
	v_mov_b64_e32 v[72:73], 0
	v_mov_b64_e32 v[74:75], 0
	v_mov_b64_e32 v[76:77], 0
	v_mov_b64_e32 v[78:79], 0
	v_mov_b64_e32 v[88:89], 0
	v_mov_b64_e32 v[90:91], 0
	v_mov_b64_e32 v[92:93], 0
	v_mov_b64_e32 v[94:95], 0
	v_mov_b64_e32 v[104:105], 0
	v_mov_b64_e32 v[106:107], 0
	v_mov_b64_e32 v[108:109], 0
	v_mov_b64_e32 v[110:111], 0
	v_mov_b64_e32 v[120:121], 0
	v_mov_b64_e32 v[122:123], 0
	v_mov_b64_e32 v[124:125], 0
	v_mov_b64_e32 v[126:127], 0
	s_branch .LBB0_207

.LBB0_552:
	s_ashr_i32 s15, s14, 31
	s_lshl_b64 s[34:35], s[14:15], 18
	v_readlane_b32 s13, v255, 26
	s_add_u32 s34, s13, s34
	v_readlane_b32 s13, v255, 27
	s_addc_u32 s35, s13, s35
	s_and_b64 s[36:37], s[4:5], exec
	s_cselect_b32 s15, s35, s47
	s_cselect_b32 s78, s34, s46
	s_ashr_i32 s13, s12, 31
	s_lshl_b64 s[36:37], s[12:13], 18
	v_readlane_b32 s70, v255, 28
	v_readlane_b32 s71, v255, 29
	s_add_u32 s36, s70, s36
	s_addc_u32 s37, s71, s37
	s_and_b64 s[70:71], s[4:5], exec
	s_cselect_b32 s13, s37, s63
	s_cselect_b32 s79, s36, s62
	s_add_u32 s46, s46, 0x20080
	s_addc_u32 s47, s47, 0
	s_add_u32 s80, s62, 0x100
	v_mov_b32_e32 v0, 0
	s_addc_u32 s81, s63, 0
	s_mov_b32 s82, -2
	v_mov_b32_e32 v1, v0
	v_mov_b64_e32 v[2:3], 0
	v_mov_b64_e32 v[4:5], 0
	v_mov_b64_e32 v[6:7], 0
	v_mov_b64_e32 v[12:13], 0
	v_mov_b64_e32 v[14:15], 0
	v_mov_b64_e32 v[20:21], 0
	v_mov_b64_e32 v[22:23], 0
	v_mov_b64_e32 v[28:29], 0
	v_mov_b64_e32 v[30:31], 0
	v_mov_b64_e32 v[36:37], 0
	v_mov_b64_e32 v[38:39], 0
	v_mov_b64_e32 v[44:45], 0
	v_mov_b64_e32 v[46:47], 0
	v_mov_b64_e32 v[52:53], 0
	v_mov_b64_e32 v[54:55], 0
	v_mov_b64_e32 v[8:9], 0
	v_mov_b64_e32 v[10:11], 0
	v_mov_b64_e32 v[16:17], 0
	v_mov_b64_e32 v[18:19], 0
	v_mov_b64_e32 v[24:25], 0
	v_mov_b64_e32 v[26:27], 0
	v_mov_b64_e32 v[32:33], 0
	v_mov_b64_e32 v[34:35], 0
	v_mov_b64_e32 v[40:41], 0
	v_mov_b64_e32 v[42:43], 0
	v_mov_b64_e32 v[48:49], 0
	v_mov_b64_e32 v[50:51], 0
	v_mov_b64_e32 v[56:57], 0
	v_mov_b64_e32 v[58:59], 0
	v_mov_b64_e32 v[60:61], 0
	v_mov_b64_e32 v[62:63], 0
	v_mov_b64_e32 v[64:65], 0
	v_mov_b64_e32 v[66:67], 0
	v_mov_b64_e32 v[68:69], 0
	v_mov_b64_e32 v[70:71], 0
	v_mov_b64_e32 v[76:77], 0
	v_mov_b64_e32 v[78:79], 0
	v_mov_b64_e32 v[84:85], 0
	v_mov_b64_e32 v[86:87], 0
	v_mov_b64_e32 v[92:93], 0
	v_mov_b64_e32 v[94:95], 0
	v_mov_b64_e32 v[100:101], 0
	v_mov_b64_e32 v[102:103], 0
	v_mov_b64_e32 v[104:105], 0
	v_mov_b64_e32 v[106:107], 0
	v_mov_b64_e32 v[112:113], 0
	v_mov_b64_e32 v[114:115], 0
	v_mov_b64_e32 v[72:73], 0
	v_mov_b64_e32 v[74:75], 0
	v_mov_b64_e32 v[80:81], 0
	v_mov_b64_e32 v[82:83], 0
	v_mov_b64_e32 v[88:89], 0
	v_mov_b64_e32 v[90:91], 0
	v_mov_b64_e32 v[96:97], 0
	v_mov_b64_e32 v[98:99], 0
	v_mov_b64_e32 v[108:109], 0
	v_mov_b64_e32 v[110:111], 0
	v_mov_b64_e32 v[116:117], 0
	v_mov_b64_e32 v[118:119], 0
	v_mov_b64_e32 v[120:121], 0
	v_mov_b64_e32 v[122:123], 0
	v_mov_b64_e32 v[124:125], 0
	v_mov_b64_e32 v[126:127], 0

.LBB0_745:
	s_ashr_i32 s35, s34, 31
	s_lshl_b64 s[36:37], s[34:35], 19
	s_add_u32 s36, s44, s36
	s_addc_u32 s37, s45, s37
	s_and_b64 s[40:41], s[8:9], exec
	v_readlane_b32 s40, v255, 38
	v_readlane_b32 s90, v255, 40
	s_cselect_b32 s35, s37, s47
	s_cselect_b32 s87, s36, s46
	s_cmp_gt_i32 s34, 63
	v_readlane_b32 s41, v255, 39
	v_readlane_b32 s91, v255, 41
	s_cselect_b32 s76, s91, s41
	s_cselect_b32 s77, s90, s40
	s_ashr_i32 s15, s14, 31
	s_lshl_b64 s[40:41], s[14:15], 19
	s_add_u32 s40, s77, s40
	s_addc_u32 s41, s76, s41
	s_and_b64 s[76:77], s[8:9], exec
	s_cselect_b32 s15, s41, s75
	s_cselect_b32 s89, s40, s74
	s_cmp_gt_i32 s60, 63
	s_cselect_b32 s76, 0x1600, 0
	s_lshl_b32 s77, s86, 8
	s_add_i32 s76, s76, s77
	v_or_b32_e32 v0, s76, v197
	v_ashrrev_i32_e32 v1, 31, v0
	s_add_u32 s46, s46, 0x40080
	v_lshlrev_b64 v[0:1], 2, v[0:1]
	s_addc_u32 s47, s47, 0
	v_lshl_add_u64 v[52:53], s[6:7], 0, v[0:1]
	v_lshl_add_u64 v[54:55], s[4:5], 0, v[0:1]
	s_add_u32 s90, s74, 0x100
	v_mov_b32_e32 v0, 0
	s_addc_u32 s91, s75, 0
	s_mov_b32 s92, -2
	v_mov_b32_e32 v1, v0
	v_mov_b64_e32 v[2:3], 0
	v_mov_b64_e32 v[8:9], 0
	v_mov_b64_e32 v[10:11], 0
	v_mov_b64_e32 v[16:17], 0
	v_mov_b64_e32 v[18:19], 0
	v_mov_b64_e32 v[24:25], 0
	v_mov_b64_e32 v[26:27], 0
	v_mov_b64_e32 v[32:33], 0
	v_mov_b64_e32 v[34:35], 0
	v_mov_b64_e32 v[40:41], 0
	v_mov_b64_e32 v[42:43], 0
	v_mov_b64_e32 v[48:49], 0
	v_mov_b64_e32 v[50:51], 0
	v_mov_b64_e32 v[68:69], 0
	v_mov_b64_e32 v[70:71], 0
	v_mov_b64_e32 v[4:5], 0
	v_mov_b64_e32 v[6:7], 0
	v_mov_b64_e32 v[12:13], 0
	v_mov_b64_e32 v[14:15], 0
	v_mov_b64_e32 v[20:21], 0
	v_mov_b64_e32 v[22:23], 0
	v_mov_b64_e32 v[28:29], 0
	v_mov_b64_e32 v[30:31], 0
	v_mov_b64_e32 v[36:37], 0
	v_mov_b64_e32 v[38:39], 0
	v_mov_b64_e32 v[44:45], 0
	v_mov_b64_e32 v[46:47], 0
	v_mov_b64_e32 v[60:61], 0
	v_mov_b64_e32 v[62:63], 0
	v_mov_b64_e32 v[80:81], 0
	v_mov_b64_e32 v[82:83], 0
	v_mov_b64_e32 v[84:85], 0
	v_mov_b64_e32 v[86:87], 0
	v_mov_b64_e32 v[92:93], 0
	v_mov_b64_e32 v[94:95], 0
	v_mov_b64_e32 v[104:105], 0
	v_mov_b64_e32 v[106:107], 0
	v_mov_b64_e32 v[112:113], 0
	v_mov_b64_e32 v[114:115], 0
	v_mov_b64_e32 v[120:121], 0
	v_mov_b64_e32 v[122:123], 0
	v_mov_b64_e32 v[128:129], 0
	v_mov_b64_e32 v[130:131], 0
	v_mov_b64_e32 v[140:141], 0
	v_mov_b64_e32 v[142:143], 0
	v_mov_b64_e32 v[148:149], 0
	v_mov_b64_e32 v[150:151], 0
	v_mov_b64_e32 v[88:89], 0
	v_mov_b64_e32 v[90:91], 0
	v_mov_b64_e32 v[96:97], 0
	v_mov_b64_e32 v[98:99], 0
	v_mov_b64_e32 v[108:109], 0
	v_mov_b64_e32 v[110:111], 0
	v_mov_b64_e32 v[116:117], 0
	v_mov_b64_e32 v[118:119], 0
	v_mov_b64_e32 v[124:125], 0
	v_mov_b64_e32 v[126:127], 0
	v_mov_b64_e32 v[132:133], 0
	v_mov_b64_e32 v[134:135], 0
	v_mov_b64_e32 v[144:145], 0
	v_mov_b64_e32 v[146:147], 0
	v_mov_b64_e32 v[152:153], 0
	v_mov_b64_e32 v[154:155], 0
	s_branch .LBB0_747

.LBB0_1065:
	s_ashr_i32 s83, s82, 31
	s_lshl_b64 s[66:67], s[82:83], 19
	s_add_u32 s88, s44, s66
	s_addc_u32 s89, s45, s67
	s_and_b64 s[66:67], s[8:9], exec
	v_readlane_b32 s66, v255, 12
	v_readlane_b32 s86, v255, 14
	s_cselect_b32 s0, s89, s47
	s_cselect_b32 s37, s88, s46
	s_cmp_gt_i32 s82, 63
	v_readlane_b32 s67, v255, 13
	v_readlane_b32 s87, v255, 15
	s_cselect_b32 s74, s87, s67
	s_cselect_b32 s75, s86, s66
	s_ashr_i32 s61, s60, 31
	s_lshl_b64 s[66:67], s[60:61], 19
	s_add_u32 s92, s75, s66
	s_addc_u32 s93, s74, s67
	s_and_b64 s[66:67], s[8:9], exec
	s_cselect_b32 s61, s93, s95
	s_cselect_b32 s66, s92, s94
	s_cmp_gt_i32 s36, 63
	s_cselect_b32 s67, 0x1400, 0
	s_lshl_b32 s74, s40, 8
	s_add_i32 s67, s67, s74
	v_or_b32_e32 v0, s67, v195
	v_ashrrev_i32_e32 v1, 31, v0
	s_add_u32 s46, s46, 0x40080
	v_lshlrev_b64 v[0:1], 2, v[0:1]
	s_addc_u32 s47, s47, 0
	v_lshl_add_u64 v[32:33], s[6:7], 0, v[0:1]
	v_lshl_add_u64 v[34:35], s[10:11], 0, v[0:1]
	s_add_u32 s67, s94, 0x100
	v_mov_b32_e32 v0, 0
	s_addc_u32 s75, s95, 0
	s_mov_b32 s83, -2
	v_mov_b32_e32 v1, v0
	v_mov_b64_e32 v[2:3], 0
	v_mov_b64_e32 v[4:5], 0
	v_mov_b64_e32 v[6:7], 0
	v_mov_b64_e32 v[16:17], 0
	v_mov_b64_e32 v[18:19], 0
	v_mov_b64_e32 v[20:21], 0
	v_mov_b64_e32 v[22:23], 0
	v_mov_b64_e32 v[36:37], 0
	v_mov_b64_e32 v[38:39], 0
	v_mov_b64_e32 v[52:53], 0
	v_mov_b64_e32 v[54:55], 0
	v_mov_b64_e32 v[84:85], 0
	v_mov_b64_e32 v[86:87], 0
	v_mov_b64_e32 v[88:89], 0
	v_mov_b64_e32 v[90:91], 0
	v_mov_b64_e32 v[8:9], 0
	v_mov_b64_e32 v[10:11], 0
	v_mov_b64_e32 v[12:13], 0
	v_mov_b64_e32 v[14:15], 0
	v_mov_b64_e32 v[24:25], 0
	v_mov_b64_e32 v[26:27], 0
	v_mov_b64_e32 v[28:29], 0
	v_mov_b64_e32 v[30:31], 0
	v_mov_b64_e32 v[76:77], 0
	v_mov_b64_e32 v[78:79], 0
	v_mov_b64_e32 v[80:81], 0
	v_mov_b64_e32 v[82:83], 0
	v_mov_b64_e32 v[92:93], 0
	v_mov_b64_e32 v[94:95], 0
	v_mov_b64_e32 v[96:97], 0
	v_mov_b64_e32 v[98:99], 0
	v_mov_b64_e32 v[104:105], 0
	v_mov_b64_e32 v[106:107], 0
	v_mov_b64_e32 v[108:109], 0
	v_mov_b64_e32 v[110:111], 0
	v_mov_b64_e32 v[120:121], 0
	v_mov_b64_e32 v[122:123], 0
	v_mov_b64_e32 v[124:125], 0
	v_mov_b64_e32 v[126:127], 0
	v_mov_b64_e32 v[140:141], 0
	v_mov_b64_e32 v[142:143], 0
	v_mov_b64_e32 v[144:145], 0
	v_mov_b64_e32 v[146:147], 0
	v_mov_b64_e32 v[156:157], 0
	v_mov_b64_e32 v[158:159], 0
	v_mov_b64_e32 v[160:161], 0
	v_mov_b64_e32 v[162:163], 0
	v_mov_b64_e32 v[112:113], 0
	v_mov_b64_e32 v[114:115], 0
	v_mov_b64_e32 v[116:117], 0
	v_mov_b64_e32 v[118:119], 0
	v_mov_b64_e32 v[128:129], 0
	v_mov_b64_e32 v[130:131], 0
	v_mov_b64_e32 v[132:133], 0
	v_mov_b64_e32 v[134:135], 0
	v_mov_b64_e32 v[148:149], 0
	v_mov_b64_e32 v[150:151], 0
	v_mov_b64_e32 v[152:153], 0
	v_mov_b64_e32 v[154:155], 0
	v_mov_b64_e32 v[164:165], 0
	v_mov_b64_e32 v[166:167], 0
	v_mov_b64_e32 v[168:169], 0
	v_mov_b64_e32 v[170:171], 0
	s_branch .LBB0_1067

.LBB0_1605:
	s_ashr_i32 s35, s34, 31
	s_lshl_b64 s[36:37], s[34:35], 19
	s_add_u32 s36, s44, s36
	s_addc_u32 s37, s45, s37
	s_and_b64 s[60:61], s[10:11], exec
	v_readlane_b32 s60, v255, 38
	v_readlane_b32 s92, v255, 40
	s_cselect_b32 s35, s37, s47
	s_cselect_b32 s86, s36, s46
	s_cmp_gt_i32 s34, 63
	v_readlane_b32 s61, v255, 39
	v_readlane_b32 s93, v255, 41
	s_cselect_b32 s82, s93, s61
	s_cselect_b32 s83, s92, s60
	s_ashr_i32 s15, s14, 31
	s_lshl_b64 s[60:61], s[14:15], 19
	s_add_u32 s60, s83, s60
	s_addc_u32 s61, s82, s61
	s_and_b64 s[82:83], s[10:11], exec
	s_cselect_b32 s15, s61, s75
	s_cselect_b32 s87, s60, s74
	s_cmp_gt_i32 s40, 63
	s_cselect_b32 s82, 0x1600, 0
	s_lshl_b32 s83, s41, 8
	s_add_i32 s82, s82, s83
	v_or_b32_e32 v0, s82, v197
	v_ashrrev_i32_e32 v1, 31, v0
	s_add_u32 s46, s46, 0x40080
	v_lshlrev_b64 v[0:1], 2, v[0:1]
	s_addc_u32 s47, s47, 0
	v_lshl_add_u64 v[52:53], s[6:7], 0, v[0:1]
	v_lshl_add_u64 v[54:55], s[4:5], 0, v[0:1]
	s_add_u32 s92, s74, 0x100
	v_mov_b32_e32 v0, 0
	s_addc_u32 s93, s75, 0
	s_mov_b32 s94, -2
	v_mov_b32_e32 v1, v0
	v_mov_b64_e32 v[2:3], 0
	v_mov_b64_e32 v[8:9], 0
	v_mov_b64_e32 v[10:11], 0
	v_mov_b64_e32 v[16:17], 0
	v_mov_b64_e32 v[18:19], 0
	v_mov_b64_e32 v[24:25], 0
	v_mov_b64_e32 v[26:27], 0
	v_mov_b64_e32 v[32:33], 0
	v_mov_b64_e32 v[34:35], 0
	v_mov_b64_e32 v[40:41], 0
	v_mov_b64_e32 v[42:43], 0
	v_mov_b64_e32 v[48:49], 0
	v_mov_b64_e32 v[50:51], 0
	v_mov_b64_e32 v[68:69], 0
	v_mov_b64_e32 v[70:71], 0
	v_mov_b64_e32 v[4:5], 0
	v_mov_b64_e32 v[6:7], 0
	v_mov_b64_e32 v[12:13], 0
	v_mov_b64_e32 v[14:15], 0
	v_mov_b64_e32 v[20:21], 0
	v_mov_b64_e32 v[22:23], 0
	v_mov_b64_e32 v[28:29], 0
	v_mov_b64_e32 v[30:31], 0
	v_mov_b64_e32 v[36:37], 0
	v_mov_b64_e32 v[38:39], 0
	v_mov_b64_e32 v[44:45], 0
	v_mov_b64_e32 v[46:47], 0
	v_mov_b64_e32 v[60:61], 0
	v_mov_b64_e32 v[62:63], 0
	v_mov_b64_e32 v[80:81], 0
	v_mov_b64_e32 v[82:83], 0
	v_mov_b64_e32 v[84:85], 0
	v_mov_b64_e32 v[86:87], 0
	v_mov_b64_e32 v[92:93], 0
	v_mov_b64_e32 v[94:95], 0
	v_mov_b64_e32 v[104:105], 0
	v_mov_b64_e32 v[106:107], 0
	v_mov_b64_e32 v[112:113], 0
	v_mov_b64_e32 v[114:115], 0
	v_mov_b64_e32 v[120:121], 0
	v_mov_b64_e32 v[122:123], 0
	v_mov_b64_e32 v[128:129], 0
	v_mov_b64_e32 v[130:131], 0
	v_mov_b64_e32 v[140:141], 0
	v_mov_b64_e32 v[142:143], 0
	v_mov_b64_e32 v[148:149], 0
	v_mov_b64_e32 v[150:151], 0
	v_mov_b64_e32 v[88:89], 0
	v_mov_b64_e32 v[90:91], 0
	v_mov_b64_e32 v[96:97], 0
	v_mov_b64_e32 v[98:99], 0
	v_mov_b64_e32 v[108:109], 0
	v_mov_b64_e32 v[110:111], 0
	v_mov_b64_e32 v[116:117], 0
	v_mov_b64_e32 v[118:119], 0
	v_mov_b64_e32 v[124:125], 0
	v_mov_b64_e32 v[126:127], 0
	v_mov_b64_e32 v[132:133], 0
	v_mov_b64_e32 v[134:135], 0
	v_mov_b64_e32 v[144:145], 0
	v_mov_b64_e32 v[146:147], 0
	v_mov_b64_e32 v[152:153], 0
	v_mov_b64_e32 v[154:155], 0
	s_branch .LBB0_1607

.LBB0_1925:
	s_ashr_i32 s83, s82, 31
	s_lshl_b64 s[66:67], s[82:83], 19
	s_add_u32 s88, s44, s66
	s_addc_u32 s89, s45, s67
	s_and_b64 s[66:67], s[10:11], exec
	v_readlane_b32 s66, v255, 12
	v_readlane_b32 s86, v255, 14
	s_cselect_b32 s0, s89, s47
	s_cselect_b32 s37, s88, s46
	s_cmp_gt_i32 s82, 63
	v_readlane_b32 s67, v255, 13
	v_readlane_b32 s87, v255, 15
	s_cselect_b32 s74, s87, s67
	s_cselect_b32 s75, s86, s66
	s_ashr_i32 s61, s60, 31
	s_lshl_b64 s[66:67], s[60:61], 19
	s_add_u32 s94, s75, s66
	s_addc_u32 s95, s74, s67
	s_and_b64 s[66:67], s[10:11], exec
	s_cselect_b32 s61, s95, s97
	s_cselect_b32 s66, s94, s96
	s_cmp_gt_i32 s36, 63
	s_cselect_b32 s67, 0x1400, 0
	s_lshl_b32 s74, s40, 8
	s_add_i32 s67, s67, s74
	v_or_b32_e32 v0, s67, v195
	v_ashrrev_i32_e32 v1, 31, v0
	s_add_u32 s46, s46, 0x40080
	v_lshlrev_b64 v[0:1], 2, v[0:1]
	s_addc_u32 s47, s47, 0
	v_lshl_add_u64 v[32:33], s[6:7], 0, v[0:1]
	v_lshl_add_u64 v[34:35], s[8:9], 0, v[0:1]
	s_add_u32 s67, s96, 0x100
	v_mov_b32_e32 v0, 0
	s_addc_u32 s75, s97, 0
	s_mov_b32 s83, -2
	v_mov_b32_e32 v1, v0
	v_mov_b64_e32 v[2:3], 0
	v_mov_b64_e32 v[4:5], 0
	v_mov_b64_e32 v[6:7], 0
	v_mov_b64_e32 v[16:17], 0
	v_mov_b64_e32 v[18:19], 0
	v_mov_b64_e32 v[20:21], 0
	v_mov_b64_e32 v[22:23], 0
	v_mov_b64_e32 v[36:37], 0
	v_mov_b64_e32 v[38:39], 0
	v_mov_b64_e32 v[52:53], 0
	v_mov_b64_e32 v[54:55], 0
	v_mov_b64_e32 v[84:85], 0
	v_mov_b64_e32 v[86:87], 0
	v_mov_b64_e32 v[88:89], 0
	v_mov_b64_e32 v[90:91], 0
	v_mov_b64_e32 v[8:9], 0
	v_mov_b64_e32 v[10:11], 0
	v_mov_b64_e32 v[12:13], 0
	v_mov_b64_e32 v[14:15], 0
	v_mov_b64_e32 v[24:25], 0
	v_mov_b64_e32 v[26:27], 0
	v_mov_b64_e32 v[28:29], 0
	v_mov_b64_e32 v[30:31], 0
	v_mov_b64_e32 v[76:77], 0
	v_mov_b64_e32 v[78:79], 0
	v_mov_b64_e32 v[80:81], 0
	v_mov_b64_e32 v[82:83], 0
	v_mov_b64_e32 v[92:93], 0
	v_mov_b64_e32 v[94:95], 0
	v_mov_b64_e32 v[96:97], 0
	v_mov_b64_e32 v[98:99], 0
	v_mov_b64_e32 v[104:105], 0
	v_mov_b64_e32 v[106:107], 0
	v_mov_b64_e32 v[108:109], 0
	v_mov_b64_e32 v[110:111], 0
	v_mov_b64_e32 v[120:121], 0
	v_mov_b64_e32 v[122:123], 0
	v_mov_b64_e32 v[124:125], 0
	v_mov_b64_e32 v[126:127], 0
	v_mov_b64_e32 v[140:141], 0
	v_mov_b64_e32 v[142:143], 0
	v_mov_b64_e32 v[144:145], 0
	v_mov_b64_e32 v[146:147], 0
	v_mov_b64_e32 v[156:157], 0
	v_mov_b64_e32 v[158:159], 0
	v_mov_b64_e32 v[160:161], 0
	v_mov_b64_e32 v[162:163], 0
	v_mov_b64_e32 v[112:113], 0
	v_mov_b64_e32 v[114:115], 0
	v_mov_b64_e32 v[116:117], 0
	v_mov_b64_e32 v[118:119], 0
	v_mov_b64_e32 v[128:129], 0
	v_mov_b64_e32 v[130:131], 0
	v_mov_b64_e32 v[132:133], 0
	v_mov_b64_e32 v[134:135], 0
	v_mov_b64_e32 v[148:149], 0
	v_mov_b64_e32 v[150:151], 0
	v_mov_b64_e32 v[152:153], 0
	v_mov_b64_e32 v[154:155], 0
	v_mov_b64_e32 v[164:165], 0
	v_mov_b64_e32 v[166:167], 0
	v_mov_b64_e32 v[168:169], 0
	v_mov_b64_e32 v[170:171], 0
	s_branch .LBB0_1927

.LBB0_2789:
	s_ashr_i32 s25, s24, 31
	s_lshl_b64 s[26:27], s[24:25], 19
	s_add_u32 s26, s44, s26
	s_addc_u32 s27, s45, s27
	s_and_b64 s[34:35], s[10:11], exec
	v_readlane_b32 s34, v255, 12
	v_readlane_b32 s48, v255, 14
	s_cselect_b32 s0, s27, s47
	s_cselect_b32 s25, s26, s46
	s_cmp_gt_i32 s24, 63
	v_readlane_b32 s35, v255, 13
	v_readlane_b32 s49, v255, 15
	s_cselect_b32 s37, s49, s35
	s_cselect_b32 s48, s48, s34
	s_ashr_i32 s23, s22, 31
	s_lshl_b64 s[34:35], s[22:23], 19
	s_add_u32 s34, s48, s34
	s_addc_u32 s35, s37, s35
	s_and_b64 s[48:49], s[10:11], exec
	s_cselect_b32 s23, s35, s53
	s_cselect_b32 s37, s34, s52
	s_cmp_gt_i32 s36, 63
	s_cselect_b32 s49, 0x1400, 0
	s_lshl_b32 s48, s40, 8
	s_add_i32 s49, s49, s48
	v_or_b32_e32 v0, s49, v195
	v_ashrrev_i32_e32 v1, 31, v0
	s_add_u32 s46, s46, 0x40080
	v_lshlrev_b64 v[0:1], 2, v[0:1]
	s_addc_u32 s47, s47, 0
	v_lshl_add_u64 v[32:33], s[6:7], 0, v[0:1]
	v_lshl_add_u64 v[34:35], s[8:9], 0, v[0:1]
	s_add_u32 s49, s52, 0x100
	v_mov_b32_e32 v0, 0
	s_addc_u32 s80, s53, 0
	s_mov_b32 s81, -2
	v_mov_b32_e32 v1, v0
	v_mov_b64_e32 v[2:3], 0
	v_mov_b64_e32 v[4:5], 0
	v_mov_b64_e32 v[6:7], 0
	v_mov_b64_e32 v[16:17], 0
	v_mov_b64_e32 v[18:19], 0
	v_mov_b64_e32 v[20:21], 0
	v_mov_b64_e32 v[22:23], 0
	v_mov_b64_e32 v[36:37], 0
	v_mov_b64_e32 v[38:39], 0
	v_mov_b64_e32 v[52:53], 0
	v_mov_b64_e32 v[54:55], 0
	v_mov_b64_e32 v[84:85], 0
	v_mov_b64_e32 v[86:87], 0
	v_mov_b64_e32 v[88:89], 0
	v_mov_b64_e32 v[90:91], 0
	v_mov_b64_e32 v[8:9], 0
	v_mov_b64_e32 v[10:11], 0
	v_mov_b64_e32 v[12:13], 0
	v_mov_b64_e32 v[14:15], 0
	v_mov_b64_e32 v[24:25], 0
	v_mov_b64_e32 v[26:27], 0
	v_mov_b64_e32 v[28:29], 0
	v_mov_b64_e32 v[30:31], 0
	v_mov_b64_e32 v[76:77], 0
	v_mov_b64_e32 v[78:79], 0
	v_mov_b64_e32 v[80:81], 0
	v_mov_b64_e32 v[82:83], 0
	v_mov_b64_e32 v[92:93], 0
	v_mov_b64_e32 v[94:95], 0
	v_mov_b64_e32 v[96:97], 0
	v_mov_b64_e32 v[98:99], 0
	v_mov_b64_e32 v[104:105], 0
	v_mov_b64_e32 v[106:107], 0
	v_mov_b64_e32 v[108:109], 0
	v_mov_b64_e32 v[110:111], 0
	v_mov_b64_e32 v[120:121], 0
	v_mov_b64_e32 v[122:123], 0
	v_mov_b64_e32 v[124:125], 0
	v_mov_b64_e32 v[126:127], 0
	v_mov_b64_e32 v[140:141], 0
	v_mov_b64_e32 v[142:143], 0
	v_mov_b64_e32 v[144:145], 0
	v_mov_b64_e32 v[146:147], 0
	v_mov_b64_e32 v[156:157], 0
	v_mov_b64_e32 v[158:159], 0
	v_mov_b64_e32 v[160:161], 0
	v_mov_b64_e32 v[162:163], 0
	v_mov_b64_e32 v[112:113], 0
	v_mov_b64_e32 v[114:115], 0
	v_mov_b64_e32 v[116:117], 0
	v_mov_b64_e32 v[118:119], 0
	v_mov_b64_e32 v[128:129], 0
	v_mov_b64_e32 v[130:131], 0
	v_mov_b64_e32 v[132:133], 0
	v_mov_b64_e32 v[134:135], 0
	v_mov_b64_e32 v[148:149], 0
	v_mov_b64_e32 v[150:151], 0
	v_mov_b64_e32 v[152:153], 0
	v_mov_b64_e32 v[154:155], 0
	v_mov_b64_e32 v[164:165], 0
	v_mov_b64_e32 v[166:167], 0
	v_mov_b64_e32 v[168:169], 0
	v_mov_b64_e32 v[170:171], 0
	s_branch .LBB0_2791

.LBB0_3137:
	s_ashr_i32 s13, s12, 31
	s_lshl_b64 s[16:17], s[12:13], 18
	v_readlane_b32 s11, v255, 26
	s_add_u32 s16, s11, s16
	v_readlane_b32 s11, v255, 27
	s_addc_u32 s17, s11, s17
	s_and_b64 s[18:19], s[6:7], exec
	s_cselect_b32 s13, s17, s25
	s_cselect_b32 s54, s16, s24
	s_ashr_i32 s11, s10, 31
	s_lshl_b64 s[18:19], s[10:11], 18
	v_readlane_b32 s34, v255, 28
	v_readlane_b32 s35, v255, 29
	s_add_u32 s18, s34, s18
	s_addc_u32 s19, s35, s19
	s_and_b64 s[34:35], s[6:7], exec
	s_cselect_b32 s11, s19, s27
	s_cselect_b32 s55, s18, s26
	s_add_u32 s24, s24, 0x20080
	s_addc_u32 s25, s25, 0
	s_add_u32 s60, s26, 0x100
	v_mov_b32_e32 v0, 0
	s_addc_u32 s61, s27, 0
	s_mov_b32 s64, -2
	v_mov_b32_e32 v1, v0
	v_mov_b64_e32 v[2:3], 0
	v_mov_b64_e32 v[4:5], 0
	v_mov_b64_e32 v[6:7], 0
	v_mov_b64_e32 v[12:13], 0
	v_mov_b64_e32 v[14:15], 0
	v_mov_b64_e32 v[20:21], 0
	v_mov_b64_e32 v[22:23], 0
	v_mov_b64_e32 v[28:29], 0
	v_mov_b64_e32 v[30:31], 0
	v_mov_b64_e32 v[36:37], 0
	v_mov_b64_e32 v[38:39], 0
	v_mov_b64_e32 v[44:45], 0
	v_mov_b64_e32 v[46:47], 0
	v_mov_b64_e32 v[52:53], 0
	v_mov_b64_e32 v[54:55], 0
	v_mov_b64_e32 v[8:9], 0
	v_mov_b64_e32 v[10:11], 0
	v_mov_b64_e32 v[16:17], 0
	v_mov_b64_e32 v[18:19], 0
	v_mov_b64_e32 v[24:25], 0
	v_mov_b64_e32 v[26:27], 0
	v_mov_b64_e32 v[32:33], 0
	v_mov_b64_e32 v[34:35], 0
	v_mov_b64_e32 v[40:41], 0
	v_mov_b64_e32 v[42:43], 0
	v_mov_b64_e32 v[48:49], 0
	v_mov_b64_e32 v[50:51], 0
	v_mov_b64_e32 v[56:57], 0
	v_mov_b64_e32 v[58:59], 0
	v_mov_b64_e32 v[60:61], 0
	v_mov_b64_e32 v[62:63], 0
	v_mov_b64_e32 v[64:65], 0
	v_mov_b64_e32 v[66:67], 0
	v_mov_b64_e32 v[68:69], 0
	v_mov_b64_e32 v[70:71], 0
	v_mov_b64_e32 v[76:77], 0
	v_mov_b64_e32 v[78:79], 0
	v_mov_b64_e32 v[84:85], 0
	v_mov_b64_e32 v[86:87], 0
	v_mov_b64_e32 v[92:93], 0
	v_mov_b64_e32 v[94:95], 0
	v_mov_b64_e32 v[100:101], 0
	v_mov_b64_e32 v[102:103], 0
	v_mov_b64_e32 v[104:105], 0
	v_mov_b64_e32 v[106:107], 0
	v_mov_b64_e32 v[112:113], 0
	v_mov_b64_e32 v[114:115], 0
	v_mov_b64_e32 v[72:73], 0
	v_mov_b64_e32 v[74:75], 0
	v_mov_b64_e32 v[80:81], 0
	v_mov_b64_e32 v[82:83], 0
	v_mov_b64_e32 v[88:89], 0
	v_mov_b64_e32 v[90:91], 0
	v_mov_b64_e32 v[96:97], 0
	v_mov_b64_e32 v[98:99], 0
	v_mov_b64_e32 v[108:109], 0
	v_mov_b64_e32 v[110:111], 0
	v_mov_b64_e32 v[116:117], 0
	v_mov_b64_e32 v[118:119], 0
	v_mov_b64_e32 v[120:121], 0
	v_mov_b64_e32 v[122:123], 0
	v_mov_b64_e32 v[124:125], 0
	v_mov_b64_e32 v[126:127], 0

.LBB0_3330:
	s_ashr_i32 s19, s18, 31
	s_lshl_b64 s[22:23], s[18:19], 19
	s_add_u32 s22, s44, s22
	s_addc_u32 s23, s45, s23
	s_and_b64 s[24:25], s[6:7], exec
	v_readlane_b32 s24, v255, 38
	v_readlane_b32 s74, v255, 40
	s_cselect_b32 s19, s23, s35
	s_cselect_b32 s73, s22, s34
	s_cmp_gt_i32 s18, 63
	v_readlane_b32 s25, v255, 39
	v_readlane_b32 s75, v255, 41
	s_cselect_b32 s40, s75, s25
	s_cselect_b32 s41, s74, s24
	s_ashr_i32 s17, s16, 31
	s_lshl_b64 s[24:25], s[16:17], 19
	s_add_u32 s24, s41, s24
	s_addc_u32 s25, s40, s25
	s_and_b64 s[40:41], s[6:7], exec
	s_cselect_b32 s17, s25, s37
	s_cselect_b32 s74, s24, s36
	s_cmp_gt_i32 s26, 63
	s_cselect_b32 s40, 0x1600, 0
	s_lshl_b32 s41, s72, 8
	s_add_i32 s40, s40, s41
	v_or_b32_e32 v0, s40, v185
	v_ashrrev_i32_e32 v1, 31, v0
	s_add_u32 s34, s34, 0x40080
	v_lshlrev_b64 v[0:1], 2, v[0:1]
	s_addc_u32 s35, s35, 0
	v_lshl_add_u64 v[104:105], s[8:9], 0, v[0:1]
	v_lshl_add_u64 v[106:107], s[4:5], 0, v[0:1]
	s_add_u32 s75, s36, 0x100
	v_mov_b32_e32 v0, 0
	s_addc_u32 s78, s37, 0
	s_mov_b32 s79, -2
	v_mov_b32_e32 v1, v0
	v_mov_b64_e32 v[2:3], 0
	v_mov_b64_e32 v[8:9], 0
	v_mov_b64_e32 v[10:11], 0
	v_mov_b64_e32 v[16:17], 0
	v_mov_b64_e32 v[18:19], 0
	v_mov_b64_e32 v[24:25], 0
	v_mov_b64_e32 v[26:27], 0
	v_mov_b64_e32 v[32:33], 0
	v_mov_b64_e32 v[34:35], 0
	v_mov_b64_e32 v[40:41], 0
	v_mov_b64_e32 v[42:43], 0
	v_mov_b64_e32 v[48:49], 0
	v_mov_b64_e32 v[50:51], 0
	v_mov_b64_e32 v[56:57], 0
	v_mov_b64_e32 v[58:59], 0
	v_mov_b64_e32 v[4:5], 0
	v_mov_b64_e32 v[6:7], 0
	v_mov_b64_e32 v[12:13], 0
	v_mov_b64_e32 v[14:15], 0
	v_mov_b64_e32 v[20:21], 0
	v_mov_b64_e32 v[22:23], 0
	v_mov_b64_e32 v[28:29], 0
	v_mov_b64_e32 v[30:31], 0
	v_mov_b64_e32 v[36:37], 0
	v_mov_b64_e32 v[38:39], 0
	v_mov_b64_e32 v[44:45], 0
	v_mov_b64_e32 v[46:47], 0
	v_mov_b64_e32 v[52:53], 0
	v_mov_b64_e32 v[54:55], 0
	v_mov_b64_e32 v[60:61], 0
	v_mov_b64_e32 v[62:63], 0
	v_mov_b64_e32 v[64:65], 0
	v_mov_b64_e32 v[66:67], 0
	v_mov_b64_e32 v[72:73], 0
	v_mov_b64_e32 v[74:75], 0
	v_mov_b64_e32 v[80:81], 0
	v_mov_b64_e32 v[82:83], 0
	v_mov_b64_e32 v[88:89], 0
	v_mov_b64_e32 v[90:91], 0
	v_mov_b64_e32 v[96:97], 0
	v_mov_b64_e32 v[98:99], 0
	v_mov_b64_e32 v[116:117], 0
	v_mov_b64_e32 v[118:119], 0
	v_mov_b64_e32 v[132:133], 0
	v_mov_b64_e32 v[134:135], 0
	v_mov_b64_e32 v[140:141], 0
	v_mov_b64_e32 v[142:143], 0
	v_mov_b64_e32 v[68:69], 0
	v_mov_b64_e32 v[70:71], 0
	v_mov_b64_e32 v[76:77], 0
	v_mov_b64_e32 v[78:79], 0
	v_mov_b64_e32 v[84:85], 0
	v_mov_b64_e32 v[86:87], 0
	v_mov_b64_e32 v[92:93], 0
	v_mov_b64_e32 v[94:95], 0
	v_mov_b64_e32 v[100:101], 0
	v_mov_b64_e32 v[102:103], 0
	v_mov_b64_e32 v[124:125], 0
	v_mov_b64_e32 v[126:127], 0
	v_mov_b64_e32 v[136:137], 0
	v_mov_b64_e32 v[138:139], 0
	v_mov_b64_e32 v[144:145], 0
	v_mov_b64_e32 v[146:147], 0
	s_branch .LBB0_3332
